# FFN-up epilogue: leading wave group's pre-epilogue alignment barrier moved down to the first store (starts its epilogue VALU under the lagging group's last MFMA segment)
# speedup vs baseline: 1.0028x; 1.0001x over previous
.Llsb_skip_9:
.LBB0_1243:
	ds_read_b128 v[150:153], v147
	ds_read_b128 v[154:157], v147 offset:1024
	ds_read_b128 v[158:161], v147 offset:2048
	ds_read_b128 v[162:165], v147 offset:3072
	ds_read_b128 v[166:169], v148
	ds_read_b128 v[170:173], v148 offset:1024
	ds_read_b128 v[174:177], v148 offset:2048
	ds_read_b128 v[178:181], v148 offset:3072
	s_add_u32 s24, s22, 0xfffc0080
	s_addc_u32 s25, s23, -1
	s_cmp_eq_u32 s51, 12
	s_cselect_b32 s27, s15, s25
	s_cselect_b32 s26, s47, s24
	s_cselect_b32 s25, s13, s50
	s_cselect_b32 s24, s48, s49
	v_lshl_add_u64 v[202:203], s[22:23], 0, v[136:137]
	s_add_i32 m0, s21, 0xc000
	ds_read_b128 v[182:185], v149
	ds_read_b128 v[186:189], v149 offset:1024
	ds_read_b128 v[190:193], v149 offset:2048
	ds_read_b128 v[194:197], v149 offset:3072
	ds_read_b128 v[198:201], v149 offset:4096
	ds_read_b128 v[206:209], v149 offset:5120
	ds_read_b128 v[210:213], v149 offset:6144
	ds_read_b128 v[214:217], v149 offset:7168
	global_load_lds_dwordx4 v[202:203], off
	v_lshl_add_u64 v[202:203], s[22:23], 0, v[138:139]
	s_add_i32 m0, s21, 0xe000
	s_nop 0
	global_load_lds_dwordx4 v[202:203], off
	s_waitcnt vmcnt(8)
	s_waitcnt lgkmcnt(0)
	s_barrier
	s_setprio 1
	s_waitcnt lgkmcnt(0)
	v_mfma_f32_16x16x32_bf16 v[124:127], v[150:153], v[182:185], v[124:127]
	v_mfma_f32_16x16x32_bf16 v[120:123], v[158:161], v[182:185], v[120:123]
	v_mfma_f32_16x16x32_bf16 v[108:111], v[150:153], v[190:193], v[108:111]
	v_mfma_f32_16x16x32_bf16 v[104:107], v[158:161], v[190:193], v[104:107]
	v_mfma_f32_16x16x32_bf16 v[92:95], v[150:153], v[198:201], v[92:95]
	v_mfma_f32_16x16x32_bf16 v[88:91], v[158:161], v[198:201], v[88:91]
	v_mfma_f32_16x16x32_bf16 v[76:79], v[150:153], v[210:213], v[76:79]
	v_mfma_f32_16x16x32_bf16 v[72:75], v[158:161], v[210:213], v[72:75]
	v_mfma_f32_16x16x32_bf16 v[124:127], v[154:157], v[186:189], v[124:127]
	v_mfma_f32_16x16x32_bf16 v[120:123], v[162:165], v[186:189], v[120:123]
	v_mfma_f32_16x16x32_bf16 v[108:111], v[154:157], v[194:197], v[108:111]
	v_mfma_f32_16x16x32_bf16 v[104:107], v[162:165], v[194:197], v[104:107]
	v_mfma_f32_16x16x32_bf16 v[92:95], v[154:157], v[206:209], v[92:95]
	v_mfma_f32_16x16x32_bf16 v[88:91], v[162:165], v[206:209], v[88:91]
	v_mfma_f32_16x16x32_bf16 v[76:79], v[154:157], v[214:217], v[76:79]
	v_mfma_f32_16x16x32_bf16 v[72:75], v[162:165], v[214:217], v[72:75]
	s_setprio 0
	s_setprio 1
	v_mfma_f32_16x16x32_bf16 v[116:119], v[166:169], v[182:185], v[116:119]
	v_mfma_f32_16x16x32_bf16 v[112:115], v[174:177], v[182:185], v[112:115]
	v_mfma_f32_16x16x32_bf16 v[100:103], v[166:169], v[190:193], v[100:103]
	v_mfma_f32_16x16x32_bf16 v[96:99], v[174:177], v[190:193], v[96:99]
	v_mfma_f32_16x16x32_bf16 v[84:87], v[166:169], v[198:201], v[84:87]
	v_mfma_f32_16x16x32_bf16 v[80:83], v[174:177], v[198:201], v[80:83]
	v_mfma_f32_16x16x32_bf16 v[68:71], v[166:169], v[210:213], v[68:71]
	v_mfma_f32_16x16x32_bf16 v[64:67], v[174:177], v[210:213], v[64:67]
	v_mfma_f32_16x16x32_bf16 v[116:119], v[170:173], v[186:189], v[116:119]
	v_mfma_f32_16x16x32_bf16 v[112:115], v[178:181], v[186:189], v[112:115]
	v_mfma_f32_16x16x32_bf16 v[100:103], v[170:173], v[194:197], v[100:103]
	v_mfma_f32_16x16x32_bf16 v[96:99], v[178:181], v[194:197], v[96:99]
	v_mfma_f32_16x16x32_bf16 v[84:87], v[170:173], v[206:209], v[84:87]
	v_mfma_f32_16x16x32_bf16 v[80:83], v[178:181], v[206:209], v[80:83]
	v_mfma_f32_16x16x32_bf16 v[68:71], v[170:173], v[214:217], v[68:71]
	v_mfma_f32_16x16x32_bf16 v[64:67], v[178:181], v[214:217], v[64:67]
	s_setprio 0
	s_barrier
	s_add_i32 s52, s43, s34
	v_lshl_add_u64 v[202:203], s[24:25], 0, v[130:131]
	s_mov_b32 m0, s52
	ds_read_b128 v[182:185], v149 offset:16384
	ds_read_b128 v[186:189], v149 offset:17408
	ds_read_b128 v[190:193], v149 offset:18432
	ds_read_b128 v[194:197], v149 offset:19456
	ds_read_b128 v[198:201], v149 offset:20480
	ds_read_b128 v[206:209], v149 offset:21504
	ds_read_b128 v[210:213], v149 offset:22528
	ds_read_b128 v[214:217], v149 offset:23552
	global_load_lds_dwordx4 v[202:203], off
	s_add_i32 m0, s52, 0x2000
	s_add_u32 s52, s24, 0x40000
	v_lshl_add_u64 v[218:219], s[24:25], 0, v[134:135]
	s_addc_u32 s53, s25, 0
	s_add_i32 s54, s44, s34
	global_load_lds_dwordx4 v[218:219], off
	v_lshl_add_u64 v[220:221], s[52:53], 0, v[130:131]
	s_mov_b32 m0, s54
	v_lshl_add_u64 v[222:223], s[26:27], 0, v[132:133]
	global_load_lds_dwordx4 v[220:221], off
	v_lshl_add_u64 v[220:221], s[52:53], 0, v[134:135]
	s_add_i32 m0, s54, 0x2000
	s_nop 0
	global_load_lds_dwordx4 v[220:221], off
	v_lshl_add_u64 v[220:221], s[26:27], 0, v[128:129]
	s_mov_b32 m0, s21
	s_nop 0
	global_load_lds_dwordx4 v[220:221], off
	s_mov_b32 m0, s35
	s_nop 0
	global_load_lds_dwordx4 v[222:223], off
	s_waitcnt vmcnt(8)
	s_waitcnt lgkmcnt(0)
	s_barrier
	s_setprio 1
	s_waitcnt lgkmcnt(0)
	v_mfma_f32_16x16x32_bf16 v[60:63], v[150:153], v[182:185], v[60:63]
	v_mfma_f32_16x16x32_bf16 v[56:59], v[158:161], v[182:185], v[56:59]
	v_mfma_f32_16x16x32_bf16 v[44:47], v[150:153], v[190:193], v[44:47]
	v_mfma_f32_16x16x32_bf16 v[40:43], v[158:161], v[190:193], v[40:43]
	v_mfma_f32_16x16x32_bf16 v[28:31], v[150:153], v[198:201], v[28:31]
	v_mfma_f32_16x16x32_bf16 v[24:27], v[158:161], v[198:201], v[24:27]
	v_mfma_f32_16x16x32_bf16 v[12:15], v[150:153], v[210:213], v[12:15]
	v_mfma_f32_16x16x32_bf16 v[8:11], v[158:161], v[210:213], v[8:11]
	v_mfma_f32_16x16x32_bf16 v[60:63], v[154:157], v[186:189], v[60:63]
	v_mfma_f32_16x16x32_bf16 v[56:59], v[162:165], v[186:189], v[56:59]
	v_mfma_f32_16x16x32_bf16 v[44:47], v[154:157], v[194:197], v[44:47]
	v_mfma_f32_16x16x32_bf16 v[40:43], v[162:165], v[194:197], v[40:43]
	v_mfma_f32_16x16x32_bf16 v[28:31], v[154:157], v[206:209], v[28:31]
	v_mfma_f32_16x16x32_bf16 v[24:27], v[162:165], v[206:209], v[24:27]
	v_mfma_f32_16x16x32_bf16 v[12:15], v[154:157], v[214:217], v[12:15]
	v_mfma_f32_16x16x32_bf16 v[8:11], v[162:165], v[214:217], v[8:11]
	s_setprio 0
	s_setprio 1
	v_mfma_f32_16x16x32_bf16 v[52:55], v[166:169], v[182:185], v[52:55]
	v_mfma_f32_16x16x32_bf16 v[48:51], v[174:177], v[182:185], v[48:51]
	v_mfma_f32_16x16x32_bf16 v[36:39], v[166:169], v[190:193], v[36:39]
	v_mfma_f32_16x16x32_bf16 v[32:35], v[174:177], v[190:193], v[32:35]
	v_mfma_f32_16x16x32_bf16 v[20:23], v[166:169], v[198:201], v[20:23]
	v_mfma_f32_16x16x32_bf16 v[16:19], v[174:177], v[198:201], v[16:19]
	v_mfma_f32_16x16x32_bf16 v[4:7], v[166:169], v[210:213], v[4:7]
	v_mfma_f32_16x16x32_bf16 v[0:3], v[174:177], v[210:213], v[0:3]
	v_mfma_f32_16x16x32_bf16 v[52:55], v[170:173], v[186:189], v[52:55]
	v_mfma_f32_16x16x32_bf16 v[48:51], v[178:181], v[186:189], v[48:51]
	v_mfma_f32_16x16x32_bf16 v[36:39], v[170:173], v[194:197], v[36:39]
	v_mfma_f32_16x16x32_bf16 v[32:35], v[178:181], v[194:197], v[32:35]
	v_mfma_f32_16x16x32_bf16 v[20:23], v[170:173], v[206:209], v[20:23]
	v_mfma_f32_16x16x32_bf16 v[16:19], v[178:181], v[206:209], v[16:19]
	v_mfma_f32_16x16x32_bf16 v[4:7], v[170:173], v[214:217], v[4:7]
	v_mfma_f32_16x16x32_bf16 v[0:3], v[178:181], v[214:217], v[0:3]
	s_setprio 0
	s_barrier
	s_add_i32 s52, 0, 0x18000
	s_add_i32 s53, 0, 0x1c000
	v_add_u32_e32 v162, s52, v145
	v_add_u32_e32 v178, s53, v145
	ds_read_b128 v[150:153], v162
	ds_read_b128 v[154:157], v162 offset:1024
	ds_read_b128 v[158:161], v162 offset:2048
	ds_read_b128 v[162:165], v162 offset:3072
	ds_read_b128 v[166:169], v178
	ds_read_b128 v[170:173], v178 offset:1024
	ds_read_b128 v[174:177], v178 offset:2048
	ds_read_b128 v[178:181], v178 offset:3072
	s_add_u32 s26, s26, 0x40000
	s_addc_u32 s27, s27, 0
	s_mov_b32 m0, s36
	v_lshl_add_u64 v[224:225], s[26:27], 0, v[128:129]
	ds_read_b128 v[182:185], v149 offset:32768
	ds_read_b128 v[186:189], v149 offset:33792
	ds_read_b128 v[190:193], v149 offset:34816
	ds_read_b128 v[194:197], v149 offset:35840
	ds_read_b128 v[198:201], v149 offset:36864
	ds_read_b128 v[206:209], v149 offset:37888
	ds_read_b128 v[210:213], v149 offset:38912
	ds_read_b128 v[214:217], v149 offset:39936
	global_load_lds_dwordx4 v[224:225], off
	v_lshl_add_u64 v[224:225], s[26:27], 0, v[132:133]
	s_mov_b32 m0, s37
	s_nop 0
	global_load_lds_dwordx4 v[224:225], off
	s_waitcnt vmcnt(8)
	s_waitcnt lgkmcnt(0)
	s_barrier
	s_setprio 1
	s_waitcnt lgkmcnt(0)
	v_mfma_f32_16x16x32_bf16 v[124:127], v[150:153], v[182:185], v[124:127]
	v_mfma_f32_16x16x32_bf16 v[120:123], v[158:161], v[182:185], v[120:123]
	v_mfma_f32_16x16x32_bf16 v[108:111], v[150:153], v[190:193], v[108:111]
	v_mfma_f32_16x16x32_bf16 v[104:107], v[158:161], v[190:193], v[104:107]
	v_mfma_f32_16x16x32_bf16 v[92:95], v[150:153], v[198:201], v[92:95]
	v_mfma_f32_16x16x32_bf16 v[88:91], v[158:161], v[198:201], v[88:91]
	v_mfma_f32_16x16x32_bf16 v[76:79], v[150:153], v[210:213], v[76:79]
	v_mfma_f32_16x16x32_bf16 v[72:75], v[158:161], v[210:213], v[72:75]
	v_mfma_f32_16x16x32_bf16 v[124:127], v[154:157], v[186:189], v[124:127]
	v_mfma_f32_16x16x32_bf16 v[120:123], v[162:165], v[186:189], v[120:123]
	v_mfma_f32_16x16x32_bf16 v[108:111], v[154:157], v[194:197], v[108:111]
	v_mfma_f32_16x16x32_bf16 v[104:107], v[162:165], v[194:197], v[104:107]
	v_mfma_f32_16x16x32_bf16 v[92:95], v[154:157], v[206:209], v[92:95]
	v_mfma_f32_16x16x32_bf16 v[88:91], v[162:165], v[206:209], v[88:91]
	v_mfma_f32_16x16x32_bf16 v[76:79], v[154:157], v[214:217], v[76:79]
	v_mfma_f32_16x16x32_bf16 v[72:75], v[162:165], v[214:217], v[72:75]
	s_setprio 0
	s_setprio 1
	v_mfma_f32_16x16x32_bf16 v[116:119], v[166:169], v[182:185], v[116:119]
	v_mfma_f32_16x16x32_bf16 v[112:115], v[174:177], v[182:185], v[112:115]
	v_mfma_f32_16x16x32_bf16 v[100:103], v[166:169], v[190:193], v[100:103]
	v_mfma_f32_16x16x32_bf16 v[96:99], v[174:177], v[190:193], v[96:99]
	v_mfma_f32_16x16x32_bf16 v[84:87], v[166:169], v[198:201], v[84:87]
	v_mfma_f32_16x16x32_bf16 v[80:83], v[174:177], v[198:201], v[80:83]
	v_mfma_f32_16x16x32_bf16 v[68:71], v[166:169], v[210:213], v[68:71]
	v_mfma_f32_16x16x32_bf16 v[64:67], v[174:177], v[210:213], v[64:67]
	v_mfma_f32_16x16x32_bf16 v[116:119], v[170:173], v[186:189], v[116:119]
	v_mfma_f32_16x16x32_bf16 v[112:115], v[178:181], v[186:189], v[112:115]
	v_mfma_f32_16x16x32_bf16 v[100:103], v[170:173], v[194:197], v[100:103]
	v_mfma_f32_16x16x32_bf16 v[96:99], v[178:181], v[194:197], v[96:99]
	v_mfma_f32_16x16x32_bf16 v[84:87], v[170:173], v[206:209], v[84:87]
	v_mfma_f32_16x16x32_bf16 v[80:83], v[178:181], v[206:209], v[80:83]
	v_mfma_f32_16x16x32_bf16 v[68:71], v[170:173], v[214:217], v[68:71]
	v_mfma_f32_16x16x32_bf16 v[64:67], v[178:181], v[214:217], v[64:67]
	s_setprio 0
	s_barrier
	s_add_i32 s26, s52, s34
	v_lshl_add_u64 v[202:203], v[202:203], 0, s[8:9]
	s_mov_b32 m0, s26
	ds_read_b128 v[182:185], v149 offset:49152
	ds_read_b128 v[186:189], v149 offset:50176
	ds_read_b128 v[190:193], v149 offset:51200
	ds_read_b128 v[194:197], v149 offset:52224
	ds_read_b128 v[198:201], v149 offset:53248
	ds_read_b128 v[206:209], v149 offset:54272
	ds_read_b128 v[210:213], v149 offset:55296
	ds_read_b128 v[214:217], v149 offset:56320
	global_load_lds_dwordx4 v[202:203], off
	s_add_i32 m0, s26, 0x2000
	s_add_u32 s24, s24, 0x40080
	v_lshl_add_u64 v[202:203], v[218:219], 0, s[8:9]
	s_addc_u32 s25, s25, 0
	s_add_i32 s26, s53, s34
	global_load_lds_dwordx4 v[202:203], off
	v_lshl_add_u64 v[202:203], s[24:25], 0, v[130:131]
	s_mov_b32 m0, s26
	s_nop 0
	global_load_lds_dwordx4 v[202:203], off
	v_lshl_add_u64 v[202:203], s[24:25], 0, v[134:135]
	s_add_i32 m0, s26, 0x2000
	s_nop 0
	global_load_lds_dwordx4 v[202:203], off
	v_lshl_add_u64 v[202:203], v[220:221], 0, s[8:9]
	s_mov_b32 m0, s40
	s_nop 0
	global_load_lds_dwordx4 v[202:203], off
	v_lshl_add_u64 v[202:203], v[222:223], 0, s[8:9]
	s_mov_b32 m0, s41
	s_nop 0
	global_load_lds_dwordx4 v[202:203], off
	s_waitcnt vmcnt(8)
	s_waitcnt lgkmcnt(0)
	s_barrier
	s_setprio 1
	s_waitcnt lgkmcnt(0)
	v_mfma_f32_16x16x32_bf16 v[60:63], v[150:153], v[182:185], v[60:63]
	v_mfma_f32_16x16x32_bf16 v[56:59], v[158:161], v[182:185], v[56:59]
	v_mfma_f32_16x16x32_bf16 v[44:47], v[150:153], v[190:193], v[44:47]
	v_mfma_f32_16x16x32_bf16 v[40:43], v[158:161], v[190:193], v[40:43]
	v_mfma_f32_16x16x32_bf16 v[28:31], v[150:153], v[198:201], v[28:31]
	v_mfma_f32_16x16x32_bf16 v[24:27], v[158:161], v[198:201], v[24:27]
	v_mfma_f32_16x16x32_bf16 v[12:15], v[150:153], v[210:213], v[12:15]
	v_mfma_f32_16x16x32_bf16 v[8:11], v[158:161], v[210:213], v[8:11]
	v_mfma_f32_16x16x32_bf16 v[60:63], v[154:157], v[186:189], v[60:63]
	v_mfma_f32_16x16x32_bf16 v[56:59], v[162:165], v[186:189], v[56:59]
	v_mfma_f32_16x16x32_bf16 v[44:47], v[154:157], v[194:197], v[44:47]
	v_mfma_f32_16x16x32_bf16 v[40:43], v[162:165], v[194:197], v[40:43]
	v_mfma_f32_16x16x32_bf16 v[28:31], v[154:157], v[206:209], v[28:31]
	v_mfma_f32_16x16x32_bf16 v[24:27], v[162:165], v[206:209], v[24:27]
	v_mfma_f32_16x16x32_bf16 v[12:15], v[154:157], v[214:217], v[12:15]
	v_mfma_f32_16x16x32_bf16 v[8:11], v[162:165], v[214:217], v[8:11]
	s_setprio 0
	s_setprio 1
	v_mfma_f32_16x16x32_bf16 v[52:55], v[166:169], v[182:185], v[52:55]
	v_mfma_f32_16x16x32_bf16 v[48:51], v[174:177], v[182:185], v[48:51]
	v_mfma_f32_16x16x32_bf16 v[36:39], v[166:169], v[190:193], v[36:39]
	v_mfma_f32_16x16x32_bf16 v[32:35], v[174:177], v[190:193], v[32:35]
	v_mfma_f32_16x16x32_bf16 v[20:23], v[166:169], v[198:201], v[20:23]
	v_mfma_f32_16x16x32_bf16 v[16:19], v[174:177], v[198:201], v[16:19]
	v_mfma_f32_16x16x32_bf16 v[4:7], v[166:169], v[210:213], v[4:7]
	v_mfma_f32_16x16x32_bf16 v[0:3], v[174:177], v[210:213], v[0:3]
	v_mfma_f32_16x16x32_bf16 v[52:55], v[170:173], v[186:189], v[52:55]
	v_mfma_f32_16x16x32_bf16 v[48:51], v[178:181], v[186:189], v[48:51]
	v_mfma_f32_16x16x32_bf16 v[36:39], v[170:173], v[194:197], v[36:39]
	v_mfma_f32_16x16x32_bf16 v[32:35], v[178:181], v[194:197], v[32:35]
	v_mfma_f32_16x16x32_bf16 v[20:23], v[170:173], v[206:209], v[20:23]
	v_mfma_f32_16x16x32_bf16 v[16:19], v[178:181], v[206:209], v[16:19]
	v_mfma_f32_16x16x32_bf16 v[4:7], v[170:173], v[214:217], v[4:7]
	v_mfma_f32_16x16x32_bf16 v[0:3], v[178:181], v[214:217], v[0:3]
	s_setprio 0
	s_barrier
	s_add_i32 s51, s51, 2
	s_add_u32 s22, s22, 0x100
	s_addc_u32 s23, s23, 0
	s_add_u32 s49, s49, 0x100
	s_addc_u32 s50, s50, 0
	s_cmp_gt_u32 s51, 13
	s_cbranch_scc0 .LBB0_1243
	v_mul_f32_e32 v151, 0xbfb8aa3b, v124
	v_mul_f32_e32 v154, 0xbfb8aa3b, v120
	v_exp_f32_e32 v151, v151
	v_exp_f32_e32 v155, v154
	v_mul_f32_e32 v154, 0xbfb8aa3b, v125
	v_exp_f32_e32 v156, v154
	v_add_f32_e32 v151, 1.0, v151
	v_rcp_f32_e32 v154, v151
	v_add_f32_e32 v151, 1.0, v155
	v_add_f32_e32 v155, 1.0, v156
	v_rcp_f32_e32 v155, v155
	v_mul_f32_e32 v156, 0xbfb8aa3b, v121
	v_exp_f32_e32 v157, v156
	v_rcp_f32_e32 v156, v151
	v_pk_mul_f32 v[124:125], v[124:125], v[154:155]
	v_mul_f32_e32 v151, 0xbfb8aa3b, v127
	v_pk_mul_f32 v[116:117], v[124:125], v[116:117]
	v_add_f32_e32 v124, 1.0, v157
	v_mul_f32_e32 v125, 0xbfb8aa3b, v122
	v_rcp_f32_e32 v157, v124
	v_mul_f32_e32 v124, 0xbfb8aa3b, v126
	v_exp_f32_e32 v125, v125
	v_exp_f32_e32 v124, v124
	v_exp_f32_e32 v151, v151
	v_mul_f32_e32 v154, 0xbfb8aa3b, v123
	v_exp_f32_e32 v155, v154
	v_add_f32_e32 v125, 1.0, v125
	v_add_f32_e32 v124, 1.0, v124
	v_rcp_f32_e32 v154, v125
	v_add_f32_e32 v125, 1.0, v151
	v_rcp_f32_e32 v124, v124
	v_rcp_f32_e32 v125, v125
	v_add_f32_e32 v151, 1.0, v155
	v_rcp_f32_e32 v155, v151
	v_pk_mul_f32 v[120:121], v[120:121], v[156:157]
	v_lshl_or_b32 v152, s46, 7, v146
	v_pk_mul_f32 v[112:113], v[120:121], v[112:113]
	v_pk_mul_f32 v[120:121], v[126:127], v[124:125]
	v_lshl_add_u32 v150, s20, 8, v144
	v_pk_mul_f32 v[118:119], v[120:121], v[118:119]
	v_pk_mul_f32 v[120:121], v[122:123], v[154:155]
	v_ashrrev_i32_e32 v153, 31, v152
	v_pk_mul_f32 v[114:115], v[120:121], v[114:115]
	v_cvt_pk_bf16_f32 v116, v116, v117
	v_cvt_pk_bf16_f32 v117, v118, v119
	v_cvt_pk_bf16_f32 v118, v112, v113
	v_mov_b64_e32 v[112:113], s[6:7]
	v_cvt_pk_bf16_f32 v119, v114, v115
	v_mad_i64_i32 v[120:121], s[22:23], v150, s45, v[112:113]
	v_lshlrev_b64 v[114:115], 1, v[152:153]
	v_lshl_add_u64 v[120:121], v[120:121], 0, v[114:115]
	s_and_b64 vcc, exec, s[10:11]
	s_cbranch_vccz .LBB0_1246
	s_barrier
.LBB0_1246:
	global_store_dwordx4 v[120:121], v[116:119], off
	s_andn2_b64 vcc, exec, s[2:3]
	s_mov_b64 s[2:3], -1
	v_mul_f32_e32 v116, 0xbfb8aa3b, v108
	v_mul_f32_e32 v117, 0xbfb8aa3b, v104
	v_mul_f32_e32 v118, 0xbfb8aa3b, v109
	v_exp_f32_e32 v116, v116
	v_exp_f32_e32 v117, v117
	v_exp_f32_e32 v118, v118
	v_add_f32_e32 v116, 1.0, v116
	v_add_f32_e32 v119, 1.0, v117
	v_add_f32_e32 v117, 1.0, v118
	v_rcp_f32_e32 v116, v116
	v_rcp_f32_e32 v117, v117
	v_mul_f32_e32 v118, 0xbfb8aa3b, v105
	v_exp_f32_e32 v120, v118
	v_rcp_f32_e32 v118, v119
	v_pk_mul_f32 v[108:109], v[108:109], v[116:117]
	v_mul_f32_e32 v116, 0xbfb8aa3b, v111
	v_pk_mul_f32 v[100:101], v[108:109], v[100:101]
	v_add_f32_e32 v108, 1.0, v120
	v_rcp_f32_e32 v119, v108
	v_mul_f32_e32 v109, 0xbfb8aa3b, v106
	v_mul_f32_e32 v108, 0xbfb8aa3b, v110
	v_exp_f32_e32 v109, v109
	v_exp_f32_e32 v108, v108
	v_exp_f32_e32 v117, v116
	v_mul_f32_e32 v116, 0xbfb8aa3b, v107
	v_pk_mul_f32 v[104:105], v[104:105], v[118:119]
	v_exp_f32_e32 v118, v116
	v_add_f32_e32 v109, 1.0, v109
	v_add_f32_e32 v108, 1.0, v108
	v_rcp_f32_e32 v116, v109
	v_add_f32_e32 v109, 1.0, v117
	v_rcp_f32_e32 v108, v108
	v_rcp_f32_e32 v109, v109
	v_add_f32_e32 v117, 1.0, v118
	v_rcp_f32_e32 v117, v117
	v_pk_mul_f32 v[104:105], v[104:105], v[96:97]
	v_pk_mul_f32 v[96:97], v[110:111], v[108:109]
	v_or_b32_e32 v108, 16, v150
	v_pk_mul_f32 v[102:103], v[96:97], v[102:103]
	v_pk_mul_f32 v[96:97], v[106:107], v[116:117]
	s_nop 0
	v_pk_mul_f32 v[106:107], v[96:97], v[98:99]
	v_cvt_pk_bf16_f32 v96, v100, v101
	v_mad_i64_i32 v[100:101], s[22:23], v108, s45, v[112:113]
	v_cvt_pk_bf16_f32 v97, v102, v103
	v_cvt_pk_bf16_f32 v98, v104, v105
	v_cvt_pk_bf16_f32 v99, v106, v107
	v_lshl_add_u64 v[100:101], v[100:101], 0, v[114:115]
	global_store_dwordx4 v[100:101], v[96:99], off
	s_nop 1
	v_mul_f32_e32 v96, 0xbfb8aa3b, v92
	v_mul_f32_e32 v97, 0xbfb8aa3b, v88
	v_mul_f32_e32 v98, 0xbfb8aa3b, v93
	v_exp_f32_e32 v96, v96
	v_exp_f32_e32 v97, v97
	v_exp_f32_e32 v98, v98
	v_add_f32_e32 v96, 1.0, v96
	v_add_f32_e32 v99, 1.0, v97
	v_add_f32_e32 v97, 1.0, v98
	v_rcp_f32_e32 v96, v96
	v_rcp_f32_e32 v97, v97
	v_mul_f32_e32 v98, 0xbfb8aa3b, v89
	v_exp_f32_e32 v100, v98
	v_rcp_f32_e32 v98, v99
	v_pk_mul_f32 v[92:93], v[92:93], v[96:97]
	v_mul_f32_e32 v96, 0xbfb8aa3b, v95
	v_pk_mul_f32 v[84:85], v[92:93], v[84:85]
	v_add_f32_e32 v92, 1.0, v100
	v_rcp_f32_e32 v99, v92
	v_mul_f32_e32 v93, 0xbfb8aa3b, v90
	v_mul_f32_e32 v92, 0xbfb8aa3b, v94
	v_exp_f32_e32 v93, v93
	v_exp_f32_e32 v92, v92
	v_exp_f32_e32 v97, v96
	v_mul_f32_e32 v96, 0xbfb8aa3b, v91
	v_pk_mul_f32 v[88:89], v[88:89], v[98:99]
	v_exp_f32_e32 v98, v96
	v_add_f32_e32 v93, 1.0, v93
	v_add_f32_e32 v92, 1.0, v92
	v_rcp_f32_e32 v96, v93
	v_add_f32_e32 v93, 1.0, v97
	v_rcp_f32_e32 v92, v92
	v_rcp_f32_e32 v93, v93
	v_add_f32_e32 v97, 1.0, v98
	v_rcp_f32_e32 v97, v97
	v_pk_mul_f32 v[88:89], v[88:89], v[80:81]
	v_pk_mul_f32 v[80:81], v[94:95], v[92:93]
	v_or_b32_e32 v92, 32, v150
	v_pk_mul_f32 v[86:87], v[80:81], v[86:87]
	v_pk_mul_f32 v[80:81], v[90:91], v[96:97]
	s_nop 0
	v_pk_mul_f32 v[90:91], v[80:81], v[82:83]
	v_cvt_pk_bf16_f32 v80, v84, v85
	v_mad_i64_i32 v[84:85], s[22:23], v92, s45, v[112:113]
	v_cvt_pk_bf16_f32 v81, v86, v87
	v_cvt_pk_bf16_f32 v82, v88, v89
	v_cvt_pk_bf16_f32 v83, v90, v91
	v_lshl_add_u64 v[84:85], v[84:85], 0, v[114:115]
	global_store_dwordx4 v[84:85], v[80:83], off
	s_nop 1
	v_mul_f32_e32 v80, 0xbfb8aa3b, v76
	v_mul_f32_e32 v81, 0xbfb8aa3b, v72
	v_mul_f32_e32 v82, 0xbfb8aa3b, v77
	v_exp_f32_e32 v80, v80
	v_exp_f32_e32 v81, v81
	v_exp_f32_e32 v82, v82
	v_add_f32_e32 v80, 1.0, v80
	v_add_f32_e32 v83, 1.0, v81
	v_add_f32_e32 v81, 1.0, v82
	v_rcp_f32_e32 v80, v80
	v_rcp_f32_e32 v81, v81
	v_mul_f32_e32 v82, 0xbfb8aa3b, v73
	v_exp_f32_e32 v84, v82
	v_rcp_f32_e32 v82, v83
	v_pk_mul_f32 v[76:77], v[76:77], v[80:81]
	v_mul_f32_e32 v80, 0xbfb8aa3b, v79
	v_pk_mul_f32 v[68:69], v[76:77], v[68:69]
	v_add_f32_e32 v76, 1.0, v84
	v_rcp_f32_e32 v83, v76
	v_mul_f32_e32 v77, 0xbfb8aa3b, v74
	v_mul_f32_e32 v76, 0xbfb8aa3b, v78
	v_exp_f32_e32 v77, v77
	v_exp_f32_e32 v76, v76
	v_exp_f32_e32 v81, v80
	v_mul_f32_e32 v80, 0xbfb8aa3b, v75
	v_pk_mul_f32 v[72:73], v[72:73], v[82:83]
	v_exp_f32_e32 v82, v80
	v_add_f32_e32 v77, 1.0, v77
	v_add_f32_e32 v76, 1.0, v76
	v_rcp_f32_e32 v80, v77
	v_add_f32_e32 v77, 1.0, v81
	v_rcp_f32_e32 v76, v76
	v_rcp_f32_e32 v77, v77
	v_add_f32_e32 v81, 1.0, v82
	v_rcp_f32_e32 v81, v81
	v_pk_mul_f32 v[72:73], v[72:73], v[64:65]
	v_pk_mul_f32 v[64:65], v[78:79], v[76:77]
	v_or_b32_e32 v76, 48, v150
	v_pk_mul_f32 v[70:71], v[64:65], v[70:71]
	v_pk_mul_f32 v[64:65], v[74:75], v[80:81]
	s_nop 0
	v_pk_mul_f32 v[74:75], v[64:65], v[66:67]
	v_cvt_pk_bf16_f32 v64, v68, v69
	v_mad_i64_i32 v[68:69], s[22:23], v76, s45, v[112:113]
	v_cvt_pk_bf16_f32 v65, v70, v71
	v_cvt_pk_bf16_f32 v66, v72, v73
	v_cvt_pk_bf16_f32 v67, v74, v75
	v_lshl_add_u64 v[68:69], v[68:69], 0, v[114:115]
	global_store_dwordx4 v[68:69], v[64:67], off
	v_add_u32_e32 v68, 0x80, v150
	s_nop 0
	v_mul_f32_e32 v64, 0xbfb8aa3b, v60
	v_mul_f32_e32 v65, 0xbfb8aa3b, v56
	v_mul_f32_e32 v66, 0xbfb8aa3b, v61
	v_exp_f32_e32 v64, v64
	v_exp_f32_e32 v65, v65
	v_exp_f32_e32 v66, v66
	v_add_f32_e32 v64, 1.0, v64
	v_add_f32_e32 v67, 1.0, v65
	v_add_f32_e32 v65, 1.0, v66
	v_rcp_f32_e32 v64, v64
	v_rcp_f32_e32 v65, v65
	v_mul_f32_e32 v66, 0xbfb8aa3b, v57
	v_exp_f32_e32 v69, v66
	v_rcp_f32_e32 v66, v67
	v_pk_mul_f32 v[60:61], v[60:61], v[64:65]
	v_mul_f32_e32 v64, 0xbfb8aa3b, v63
	v_pk_mul_f32 v[52:53], v[60:61], v[52:53]
	v_add_f32_e32 v60, 1.0, v69
	v_rcp_f32_e32 v67, v60
	v_mul_f32_e32 v61, 0xbfb8aa3b, v58
	v_mul_f32_e32 v60, 0xbfb8aa3b, v62
	v_exp_f32_e32 v61, v61
	v_exp_f32_e32 v60, v60
	v_exp_f32_e32 v65, v64
	v_mul_f32_e32 v64, 0xbfb8aa3b, v59
	v_pk_mul_f32 v[56:57], v[56:57], v[66:67]
	v_exp_f32_e32 v66, v64
	v_add_f32_e32 v61, 1.0, v61
	v_add_f32_e32 v60, 1.0, v60
	v_rcp_f32_e32 v64, v61
	v_add_f32_e32 v61, 1.0, v65
	v_rcp_f32_e32 v60, v60
	v_rcp_f32_e32 v61, v61
	v_add_f32_e32 v65, 1.0, v66
	v_rcp_f32_e32 v65, v65
	v_pk_mul_f32 v[56:57], v[56:57], v[48:49]
	v_pk_mul_f32 v[48:49], v[62:63], v[60:61]
	s_nop 0
	v_pk_mul_f32 v[54:55], v[48:49], v[54:55]
	v_pk_mul_f32 v[48:49], v[58:59], v[64:65]
	s_nop 0
	v_pk_mul_f32 v[58:59], v[48:49], v[50:51]
	v_cvt_pk_bf16_f32 v48, v52, v53
	v_mad_i64_i32 v[52:53], s[22:23], v68, s45, v[112:113]
	v_cvt_pk_bf16_f32 v49, v54, v55
	v_cvt_pk_bf16_f32 v50, v56, v57
	v_cvt_pk_bf16_f32 v51, v58, v59
	v_lshl_add_u64 v[52:53], v[52:53], 0, v[114:115]
	global_store_dwordx4 v[52:53], v[48:51], off
	s_nop 1
	v_mul_f32_e32 v48, 0xbfb8aa3b, v44
	v_mul_f32_e32 v49, 0xbfb8aa3b, v40
	v_mul_f32_e32 v50, 0xbfb8aa3b, v45
	v_exp_f32_e32 v48, v48
	v_exp_f32_e32 v49, v49
	v_exp_f32_e32 v50, v50
	v_add_f32_e32 v48, 1.0, v48
	v_add_f32_e32 v51, 1.0, v49
	v_add_f32_e32 v49, 1.0, v50
	v_rcp_f32_e32 v48, v48
	v_rcp_f32_e32 v49, v49
	v_mul_f32_e32 v50, 0xbfb8aa3b, v41
	v_exp_f32_e32 v52, v50
	v_rcp_f32_e32 v50, v51
	v_pk_mul_f32 v[44:45], v[44:45], v[48:49]
	v_mul_f32_e32 v48, 0xbfb8aa3b, v47
	v_pk_mul_f32 v[36:37], v[44:45], v[36:37]
	v_add_f32_e32 v44, 1.0, v52
	v_rcp_f32_e32 v51, v44
	v_mul_f32_e32 v45, 0xbfb8aa3b, v42
	v_mul_f32_e32 v44, 0xbfb8aa3b, v46
	v_exp_f32_e32 v45, v45
	v_exp_f32_e32 v44, v44
	v_exp_f32_e32 v49, v48
	v_mul_f32_e32 v48, 0xbfb8aa3b, v43
	v_pk_mul_f32 v[40:41], v[40:41], v[50:51]
	v_exp_f32_e32 v50, v48
	v_add_f32_e32 v45, 1.0, v45
	v_add_f32_e32 v44, 1.0, v44
	v_rcp_f32_e32 v48, v45
	v_add_f32_e32 v45, 1.0, v49
	v_rcp_f32_e32 v44, v44
	v_rcp_f32_e32 v45, v45
	v_add_f32_e32 v49, 1.0, v50
	v_rcp_f32_e32 v49, v49
	v_pk_mul_f32 v[40:41], v[40:41], v[32:33]
	v_pk_mul_f32 v[32:33], v[46:47], v[44:45]
	v_add_u32_e32 v44, 0x90, v150
	v_pk_mul_f32 v[38:39], v[32:33], v[38:39]
	v_pk_mul_f32 v[32:33], v[42:43], v[48:49]
	s_nop 0
	v_pk_mul_f32 v[42:43], v[32:33], v[34:35]
	v_cvt_pk_bf16_f32 v32, v36, v37
	v_mad_i64_i32 v[36:37], s[22:23], v44, s45, v[112:113]
	v_cvt_pk_bf16_f32 v33, v38, v39
	v_cvt_pk_bf16_f32 v34, v40, v41
	v_cvt_pk_bf16_f32 v35, v42, v43
	v_lshl_add_u64 v[36:37], v[36:37], 0, v[114:115]
	global_store_dwordx4 v[36:37], v[32:35], off
	s_nop 1
	v_mul_f32_e32 v32, 0xbfb8aa3b, v28
	v_mul_f32_e32 v33, 0xbfb8aa3b, v24
	v_mul_f32_e32 v34, 0xbfb8aa3b, v29
	v_exp_f32_e32 v32, v32
	v_exp_f32_e32 v33, v33
	v_exp_f32_e32 v34, v34
	v_add_f32_e32 v32, 1.0, v32
	v_add_f32_e32 v35, 1.0, v33
	v_add_f32_e32 v33, 1.0, v34
	v_rcp_f32_e32 v32, v32
	v_rcp_f32_e32 v33, v33
	v_mul_f32_e32 v34, 0xbfb8aa3b, v25
	v_exp_f32_e32 v36, v34
	v_rcp_f32_e32 v34, v35
	v_pk_mul_f32 v[28:29], v[28:29], v[32:33]
	v_mul_f32_e32 v32, 0xbfb8aa3b, v31
	v_pk_mul_f32 v[20:21], v[28:29], v[20:21]
	v_add_f32_e32 v28, 1.0, v36
	v_rcp_f32_e32 v35, v28
	v_mul_f32_e32 v29, 0xbfb8aa3b, v26
	v_mul_f32_e32 v28, 0xbfb8aa3b, v30
	v_exp_f32_e32 v29, v29
	v_exp_f32_e32 v28, v28
	v_exp_f32_e32 v33, v32
	v_mul_f32_e32 v32, 0xbfb8aa3b, v27
	v_pk_mul_f32 v[24:25], v[24:25], v[34:35]
	v_exp_f32_e32 v34, v32
	v_add_f32_e32 v29, 1.0, v29
	v_add_f32_e32 v28, 1.0, v28
	v_rcp_f32_e32 v32, v29
	v_add_f32_e32 v29, 1.0, v33
	v_rcp_f32_e32 v28, v28
	v_rcp_f32_e32 v29, v29
	v_add_f32_e32 v33, 1.0, v34
	v_rcp_f32_e32 v33, v33
	v_pk_mul_f32 v[24:25], v[24:25], v[16:17]
	v_pk_mul_f32 v[16:17], v[30:31], v[28:29]
	v_add_u32_e32 v28, 0xa0, v150
	v_pk_mul_f32 v[22:23], v[16:17], v[22:23]
	v_pk_mul_f32 v[16:17], v[26:27], v[32:33]
	s_nop 0
	v_pk_mul_f32 v[26:27], v[16:17], v[18:19]
	v_cvt_pk_bf16_f32 v16, v20, v21
	v_mad_i64_i32 v[20:21], s[22:23], v28, s45, v[112:113]
	v_cvt_pk_bf16_f32 v17, v22, v23
	v_cvt_pk_bf16_f32 v18, v24, v25
	v_cvt_pk_bf16_f32 v19, v26, v27
	v_lshl_add_u64 v[20:21], v[20:21], 0, v[114:115]
	global_store_dwordx4 v[20:21], v[16:19], off
	s_nop 1
	v_mul_f32_e32 v16, 0xbfb8aa3b, v12
	v_mul_f32_e32 v17, 0xbfb8aa3b, v8
	v_mul_f32_e32 v18, 0xbfb8aa3b, v13
	v_exp_f32_e32 v16, v16
	v_exp_f32_e32 v17, v17
	v_exp_f32_e32 v18, v18
	v_add_f32_e32 v16, 1.0, v16
	v_add_f32_e32 v19, 1.0, v17
	v_add_f32_e32 v17, 1.0, v18
	v_rcp_f32_e32 v16, v16
	v_rcp_f32_e32 v17, v17
	v_mul_f32_e32 v18, 0xbfb8aa3b, v9
	v_exp_f32_e32 v20, v18
	v_rcp_f32_e32 v18, v19
	v_pk_mul_f32 v[12:13], v[12:13], v[16:17]
	v_mul_f32_e32 v16, 0xbfb8aa3b, v15
	v_pk_mul_f32 v[4:5], v[12:13], v[4:5]
	v_add_f32_e32 v12, 1.0, v20
	v_rcp_f32_e32 v19, v12
	v_mul_f32_e32 v13, 0xbfb8aa3b, v10
	v_mul_f32_e32 v12, 0xbfb8aa3b, v14
	v_exp_f32_e32 v13, v13
	v_exp_f32_e32 v12, v12
	v_exp_f32_e32 v17, v16
	v_mul_f32_e32 v16, 0xbfb8aa3b, v11
	v_pk_mul_f32 v[8:9], v[8:9], v[18:19]
	v_exp_f32_e32 v18, v16
	v_add_f32_e32 v13, 1.0, v13
	v_add_f32_e32 v12, 1.0, v12
	v_rcp_f32_e32 v16, v13
	v_add_f32_e32 v13, 1.0, v17
	v_rcp_f32_e32 v12, v12
	v_rcp_f32_e32 v13, v13
	v_add_f32_e32 v17, 1.0, v18
	v_rcp_f32_e32 v17, v17
	v_pk_mul_f32 v[8:9], v[8:9], v[0:1]
	v_pk_mul_f32 v[0:1], v[14:15], v[12:13]
	v_add_u32_e32 v12, 0xb0, v150
	v_pk_mul_f32 v[6:7], v[0:1], v[6:7]
	v_pk_mul_f32 v[0:1], v[10:11], v[16:17]
	s_nop 0
	v_pk_mul_f32 v[10:11], v[0:1], v[2:3]
	v_cvt_pk_bf16_f32 v0, v4, v5
	v_mad_i64_i32 v[4:5], s[22:23], v12, s45, v[112:113]
	v_cvt_pk_bf16_f32 v1, v6, v7
	v_cvt_pk_bf16_f32 v2, v8, v9
	v_cvt_pk_bf16_f32 v3, v10, v11
	v_lshl_add_u64 v[4:5], v[4:5], 0, v[114:115]
	global_store_dwordx4 v[4:5], v[0:3], off
	s_cbranch_vccnz .LBB0_1235
	s_andn2_b64 vcc, exec, s[0:1]
	s_cbranch_vccnz .LBB0_1234
	v_writelane_b32 v255, 1, 53
	s_branch .LBB0_1234
